# shared-hot-barrier-routine-for-seams-1plus
# speedup vs baseline: 1.0228x; 1.0228x over previous
.LBB0_175:
.LBB0_176:
	s_cmp_gt_i32 s73, 2
	s_cselect_b64 s[0:1], -1, 0
	s_and_b64 s[4:5], s[8:9], s[0:1]
	s_andn2_b64 vcc, exec, s[4:5]
	s_cbranch_vccnz .LBB0_240
	s_cmp_gt_i32 s72, -1
	s_mov_b64 s[4:5], -1
	s_cbranch_scc0 .LBB0_227
	s_waitcnt vmcnt(0)
	v_cmp_eq_u32_e32 vcc, 0, v143
	s_waitcnt vmcnt(0)
	s_barrier
	s_and_saveexec_b64 s[4:5], vcc
	s_cbranch_execz .LBB0_226
	s_mov_b32 s98, 1
	s_branch .Lsbar
	v_readlane_b32 s3, v242, 11
	s_waitcnt vmcnt(0) expcnt(0) lgkmcnt(0)
	s_nop 0
	v_mov_b32_e32 v1, s3
	ds_read_b32 v3, v1
	ds_read_b32 v1, v1 offset:4
	s_waitcnt lgkmcnt(1)
	v_cmp_ne_u32_e32 vcc, 0, v3
	s_cbranch_vccnz .LBB0_194
	s_add_u32 s6, s70, 0x1000
	s_addc_u32 s7, s71, 0
	s_add_u32 s8, s70, 0x1100
	s_addc_u32 s9, s71, 0
	s_add_u32 s10, s70, 0x1200
	v_readlane_b32 s3, v242, 8
	s_addc_u32 s11, s71, 0
	s_mul_i32 s3, s75, s3
	s_add_u32 s12, s70, 0x1300
	s_mul_i32 s3, s3, s74
	s_addc_u32 s13, s71, 0
	s_mov_b32 s28, 1
	v_mov_b32_e32 v17, 0
	s_branch .LBB0_182

.LBB0_361:
	s_cmp_gt_i32 s73, 4
	s_cselect_b64 s[0:1], -1, 0
	s_and_b64 s[4:5], s[8:9], s[0:1]
	s_andn2_b64 vcc, exec, s[4:5]
	s_cbranch_vccnz .LBB0_425
	s_cmp_gt_i32 s72, -1
	s_mov_b64 s[4:5], -1
	s_cbranch_scc0 .LBB0_412
	s_waitcnt vmcnt(0)
	v_cmp_eq_u32_e32 vcc, 0, v143
	s_waitcnt vmcnt(0)
	s_barrier
	s_and_saveexec_b64 s[4:5], vcc
	s_cbranch_execz .LBB0_411
	s_mov_b32 s98, 2
	s_branch .Lsbar
	v_readlane_b32 s3, v242, 11
	s_waitcnt vmcnt(0) expcnt(0) lgkmcnt(0)
	s_nop 0
	v_mov_b32_e32 v1, s3
	ds_read_b32 v3, v1
	ds_read_b32 v1, v1 offset:4
	s_waitcnt lgkmcnt(1)
	v_cmp_ne_u32_e32 vcc, 0, v3
	s_cbranch_vccnz .LBB0_379
	s_add_u32 s8, s70, 0x1000
	s_addc_u32 s9, s71, 0
	s_add_u32 s10, s70, 0x1100
	s_addc_u32 s11, s71, 0
	s_add_u32 s12, s70, 0x1200
	v_readlane_b32 s3, v242, 8
	s_addc_u32 s13, s71, 0
	s_mul_i32 s3, s75, s3
	s_add_u32 s22, s70, 0x1300
	s_mul_i32 s3, s3, s74
	s_addc_u32 s23, s71, 0
	s_mov_b32 s30, 1
	v_mov_b32_e32 v17, 0
	s_branch .LBB0_367

.LBB0_464:
	s_cmp_gt_i32 s73, 5
	s_cselect_b64 s[0:1], -1, 0
	s_and_b64 s[4:5], s[8:9], s[0:1]
	s_andn2_b64 vcc, exec, s[4:5]
	s_cbranch_vccnz .LBB0_528
	s_cmp_gt_i32 s72, -1
	s_mov_b64 s[4:5], -1
	s_cbranch_scc0 .LBB0_515
	s_waitcnt vmcnt(0)
	v_cmp_eq_u32_e32 vcc, 0, v143
	s_waitcnt vmcnt(0)
	s_barrier
	s_and_saveexec_b64 s[4:5], vcc
	s_cbranch_execz .LBB0_514
	s_mov_b32 s98, 3
	s_branch .Lsbar
	v_readlane_b32 s3, v242, 11
	s_waitcnt vmcnt(0) expcnt(0) lgkmcnt(0)
	s_nop 0
	v_mov_b32_e32 v1, s3
	ds_read_b32 v3, v1
	ds_read_b32 v1, v1 offset:4
	s_waitcnt lgkmcnt(1)
	v_cmp_ne_u32_e32 vcc, 0, v3
	s_cbranch_vccnz .LBB0_482
	s_add_u32 s8, s70, 0x1000
	s_addc_u32 s9, s71, 0
	s_add_u32 s10, s70, 0x1100
	s_addc_u32 s11, s71, 0
	s_add_u32 s12, s70, 0x1200
	v_readlane_b32 s3, v242, 8
	s_addc_u32 s13, s71, 0
	s_mul_i32 s3, s75, s3
	s_add_u32 s20, s70, 0x1300
	s_mul_i32 s3, s3, s74
	s_addc_u32 s21, s71, 0
	s_mov_b32 s28, 1
	v_mov_b32_e32 v17, 0
	s_branch .LBB0_470

.LBB0_541:
	s_cmp_gt_i32 s73, 6
	s_cselect_b64 s[4:5], -1, 0
	s_and_b64 s[0:1], s[0:1], s[4:5]
	s_andn2_b64 vcc, exec, s[0:1]
	s_cbranch_vccnz .LBB0_605
	s_cmp_gt_i32 s72, -1
	s_mov_b64 s[0:1], -1
	s_cbranch_scc0 .LBB0_592
	s_waitcnt vmcnt(0)
	v_cmp_eq_u32_e32 vcc, 0, v143
	s_waitcnt vmcnt(0)
	s_barrier
	s_and_saveexec_b64 s[0:1], vcc
	s_cbranch_execz .LBB0_591
	s_mov_b32 s98, 4
	s_branch .Lsbar
	v_readlane_b32 s3, v242, 11
	s_waitcnt vmcnt(0) expcnt(0) lgkmcnt(0)
	s_nop 0
	v_mov_b32_e32 v1, s3
	ds_read_b32 v3, v1
	ds_read_b32 v1, v1 offset:4
	s_waitcnt lgkmcnt(1)
	v_cmp_ne_u32_e32 vcc, 0, v3
	s_cbranch_vccnz .LBB0_559
	s_add_u32 s8, s70, 0x1000
	s_addc_u32 s9, s71, 0
	s_add_u32 s10, s70, 0x1100
	s_addc_u32 s11, s71, 0
	s_add_u32 s12, s70, 0x1200
	v_readlane_b32 s3, v242, 8
	s_addc_u32 s13, s71, 0
	s_mul_i32 s3, s75, s3
	s_add_u32 s20, s70, 0x1300
	s_mul_i32 s3, s3, s74
	s_addc_u32 s21, s71, 0
	s_mov_b32 s28, 1
	v_mov_b32_e32 v17, 0
	s_branch .LBB0_547

.LBB0_622:
	s_cmp_gt_i32 s73, 7
	s_cselect_b64 s[0:1], -1, 0
	s_and_b64 s[4:5], s[4:5], s[0:1]
	s_andn2_b64 vcc, exec, s[4:5]
	s_cbranch_vccnz .LBB0_686
	s_cmp_gt_i32 s72, -1
	s_mov_b64 s[4:5], -1
	s_cbranch_scc0 .LBB0_673
	s_waitcnt vmcnt(0)
	v_cmp_eq_u32_e32 vcc, 0, v143
	s_waitcnt vmcnt(0)
	s_barrier
	s_and_saveexec_b64 s[4:5], vcc
	s_cbranch_execz .LBB0_672
	s_mov_b32 s98, 5
	s_branch .Lsbar
	v_readlane_b32 s3, v242, 11
	s_waitcnt vmcnt(0) expcnt(0) lgkmcnt(0)
	s_nop 0
	v_mov_b32_e32 v1, s3
	ds_read_b32 v3, v1
	ds_read_b32 v1, v1 offset:4
	s_waitcnt lgkmcnt(1)
	v_cmp_ne_u32_e32 vcc, 0, v3
	s_cbranch_vccnz .LBB0_640
	s_add_u32 s6, s70, 0x1000
	s_addc_u32 s7, s71, 0
	s_add_u32 s8, s70, 0x1100
	s_addc_u32 s9, s71, 0
	s_add_u32 s10, s70, 0x1200
	v_readlane_b32 s3, v242, 8
	s_addc_u32 s11, s71, 0
	s_mul_i32 s3, s75, s3
	s_add_u32 s12, s70, 0x1300
	s_mul_i32 s3, s3, s74
	s_addc_u32 s13, s71, 0
	s_mov_b32 s26, 1
	v_mov_b32_e32 v17, 0
	s_branch .LBB0_628

.LBB0_725:
	s_cmp_gt_i32 s73, 8
	s_cselect_b64 s[0:1], -1, 0
	s_and_b64 s[4:5], s[6:7], s[0:1]
	v_readlane_b32 s14, v242, 47
	s_andn2_b64 vcc, exec, s[4:5]
	v_readlane_b32 s15, v242, 48
	s_cbranch_vccnz .LBB0_789
	s_cmp_gt_i32 s72, -1
	s_mov_b64 s[4:5], -1
	s_cbranch_scc0 .LBB0_776
	s_waitcnt vmcnt(0)
	v_cmp_eq_u32_e32 vcc, 0, v143
	s_waitcnt vmcnt(0)
	s_barrier
	s_and_saveexec_b64 s[4:5], vcc
	s_cbranch_execz .LBB0_775
	s_mov_b32 s98, 6
	s_branch .Lsbar
	v_readlane_b32 s3, v242, 11
	s_waitcnt vmcnt(0) expcnt(0) lgkmcnt(0)
	s_nop 0
	v_mov_b32_e32 v1, s3
	ds_read_b32 v3, v1
	ds_read_b32 v1, v1 offset:4
	s_waitcnt lgkmcnt(1)
	v_cmp_ne_u32_e32 vcc, 0, v3
	s_cbranch_vccnz .LBB0_743
	s_add_u32 s6, s70, 0x1000
	s_addc_u32 s7, s71, 0
	s_add_u32 s8, s70, 0x1100
	s_addc_u32 s9, s71, 0
	s_add_u32 s10, s70, 0x1200
	v_readlane_b32 s3, v242, 8
	s_addc_u32 s11, s71, 0
	s_mul_i32 s3, s75, s3
	s_add_u32 s12, s70, 0x1300
	s_mul_i32 s3, s3, s74
	s_addc_u32 s13, s71, 0
	s_mov_b32 s24, 1
	v_mov_b32_e32 v17, 0
	s_branch .LBB0_731

.Lsbar:
	v_readlane_b32 s99, v242, 11
	v_readlane_b32 s100, v242, 30
	s_add_u32 s101, s98, 1
	s_nop 0
	v_mov_b32_e32 v244, s99
	ds_read_b32 v245, v244
	ds_read_b32 v246, v244 offset:4
	s_lshl_b32 s100, s100, 8
	s_add_u32 s100, s100, 0x1400
	v_mov_b32_e32 v247, s100
	v_mov_b32_e32 v248, 1
	global_atomic_add v249, v247, v248, s[70:71] sc0
	s_waitcnt lgkmcnt(0)
	v_mul_lo_u32 v245, v245, s101
	v_mul_lo_u32 v246, v246, s101
	v_mov_b32_e32 v250, 0x3500
	v_mov_b32_e32 v251, s98
	s_mov_b32 s99, 0
	s_waitcnt vmcnt(0)
	v_add_u32_e32 v249, 1, v249
	v_cmp_eq_u32_e32 vcc, v249, v245
	s_cbranch_vccz .Lsbar_poll
	buffer_wbl2 sc1
	s_waitcnt vmcnt(0)
	v_mov_b32_e32 v247, 0x3400
	global_atomic_add v249, v247, v248, s[70:71] sc0
	s_waitcnt vmcnt(0)
	v_add_u32_e32 v249, 1, v249
	v_cmp_eq_u32_e32 vcc, v249, v246
	s_cbranch_vccz .Lsbar_poll
	global_atomic_add v250, v248, s[70:71]
	s_branch .Lsbar_acq
.Lsbar_poll:
	global_load_dword v252, v250, s[70:71] sc1
	s_waitcnt vmcnt(0)
	v_cmp_ne_u32_e32 vcc, v252, v251
	s_cbranch_vccnz .Lsbar_acq
	s_sleep 1
	s_add_u32 s99, s99, 1
	s_cmp_lt_u32 s99, 0x100000
	s_cbranch_scc1 .Lsbar_poll
.Lsbar_acq:
	s_waitcnt vmcnt(0)
	buffer_inv sc1
	s_waitcnt vmcnt(0)
	s_cmp_eq_u32 s98, 1
	s_cbranch_scc1 .LBB0_226
	s_cmp_eq_u32 s98, 2
	s_cbranch_scc1 .LBB0_411
	s_cmp_eq_u32 s98, 3
	s_cbranch_scc1 .LBB0_514
	s_cmp_eq_u32 s98, 4
	s_cbranch_scc1 .LBB0_591
	s_cmp_eq_u32 s98, 5
	s_cbranch_scc1 .LBB0_672
	s_cmp_eq_u32 s98, 6
	s_cbranch_scc1 .LBB0_775
	s_cmp_eq_u32 s98, 7
	s_cbranch_scc1 .LBB0_846
	s_cmp_eq_u32 s98, 8
	s_cbranch_scc1 .LBB0_1096
	s_cmp_eq_u32 s98, 9
	s_cbranch_scc1 .LBB0_1229
	s_cmp_eq_u32 s98, 10
	s_cbranch_scc1 .LBB0_1332
	s_cmp_eq_u32 s98, 11
	s_cbranch_scc1 .LBB0_1403
	s_cmp_eq_u32 s98, 12
	s_cbranch_scc1 .LBB0_1484
	s_branch .LBB0_1588

.LBB0_796:
	s_cmp_gt_i32 s73, 9
	s_cselect_b64 s[4:5], -1, 0
	s_and_b64 s[0:1], s[0:1], s[4:5]
	s_andn2_b64 vcc, exec, s[0:1]
	s_cbranch_vccnz .LBB0_860
	s_cmp_gt_i32 s72, -1
	s_mov_b64 s[0:1], -1
	s_cbranch_scc0 .LBB0_847
	s_waitcnt vmcnt(0)
	v_cmp_eq_u32_e32 vcc, 0, v143
	s_waitcnt vmcnt(0)
	s_barrier
	s_and_saveexec_b64 s[0:1], vcc
	s_cbranch_execz .LBB0_846
	s_mov_b32 s98, 7
	s_branch .Lsbar
	v_readlane_b32 s3, v242, 11
	s_waitcnt vmcnt(0) expcnt(0) lgkmcnt(0)
	s_nop 0
	v_mov_b32_e32 v1, s3
	ds_read_b32 v3, v1
	ds_read_b32 v1, v1 offset:4
	s_waitcnt lgkmcnt(1)
	v_cmp_ne_u32_e32 vcc, 0, v3
	s_cbranch_vccnz .LBB0_814
	s_add_u32 s6, s70, 0x1000
	s_addc_u32 s7, s71, 0
	s_add_u32 s8, s70, 0x1100
	s_addc_u32 s9, s71, 0
	s_add_u32 s10, s70, 0x1200
	v_readlane_b32 s3, v242, 8
	s_addc_u32 s11, s71, 0
	s_mul_i32 s3, s75, s3
	s_add_u32 s12, s70, 0x1300
	s_mul_i32 s3, s3, s74
	s_addc_u32 s13, s71, 0
	s_mov_b32 s24, 1
	v_mov_b32_e32 v17, 0
	s_branch .LBB0_802

.LBB0_1046:
	s_cmp_gt_i32 s73, 10
	s_cselect_b64 s[0:1], -1, 0
	s_and_b64 s[4:5], s[90:91], s[0:1]
	s_andn2_b64 vcc, exec, s[4:5]
	s_cbranch_vccnz .LBB0_1110
	s_cmp_gt_i32 s72, -1
	s_mov_b64 s[4:5], -1
	s_cbranch_scc0 .LBB0_1097
	s_waitcnt vmcnt(0)
	v_cmp_eq_u32_e32 vcc, 0, v143
	s_waitcnt vmcnt(0)
	s_barrier
	s_and_saveexec_b64 s[4:5], vcc
	s_cbranch_execz .LBB0_1096
	s_mov_b32 s98, 8
	s_branch .Lsbar
	v_readlane_b32 s3, v242, 11
	s_waitcnt vmcnt(0) expcnt(0) lgkmcnt(0)
	s_nop 0
	v_mov_b32_e32 v1, s3
	ds_read_b32 v3, v1
	ds_read_b32 v1, v1 offset:4
	s_waitcnt lgkmcnt(1)
	v_cmp_ne_u32_e32 vcc, 0, v3
	s_cbranch_vccnz .LBB0_1064
	s_add_u32 s6, s70, 0x1000
	s_addc_u32 s7, s71, 0
	s_add_u32 s8, s70, 0x1100
	s_addc_u32 s9, s71, 0
	s_add_u32 s10, s70, 0x1200
	v_readlane_b32 s3, v242, 8
	s_addc_u32 s11, s71, 0
	s_mul_i32 s3, s75, s3
	s_add_u32 s12, s70, 0x1300
	s_mul_i32 s3, s3, s74
	s_addc_u32 s13, s71, 0
	s_mov_b32 s20, 1
	v_mov_b32_e32 v17, 0
	s_branch .LBB0_1052

.LBB0_1179:
	s_cmp_gt_i32 s73, 11
	s_cselect_b64 s[0:1], -1, 0
	s_and_b64 s[4:5], s[56:57], s[0:1]
	s_andn2_b64 vcc, exec, s[4:5]
	s_cbranch_vccnz .LBB0_1243
	s_cmp_gt_i32 s72, -1
	s_mov_b64 s[4:5], -1
	s_cbranch_scc0 .LBB0_1230
	s_waitcnt vmcnt(0)
	v_cmp_eq_u32_e32 vcc, 0, v143
	s_waitcnt vmcnt(0) lgkmcnt(0)
	s_barrier
	s_and_saveexec_b64 s[4:5], vcc
	s_cbranch_execz .LBB0_1229
	s_mov_b32 s98, 9
	s_branch .Lsbar
	v_readlane_b32 s3, v242, 11
	s_waitcnt vmcnt(0) expcnt(0) lgkmcnt(0)
	s_nop 0
	v_mov_b32_e32 v1, s3
	ds_read_b32 v3, v1
	ds_read_b32 v1, v1 offset:4
	s_waitcnt lgkmcnt(1)
	v_cmp_ne_u32_e32 vcc, 0, v3
	s_cbranch_vccnz .LBB0_1197
	s_add_u32 s6, s70, 0x1000
	s_addc_u32 s7, s71, 0
	s_add_u32 s8, s70, 0x1100
	s_addc_u32 s9, s71, 0
	s_add_u32 s10, s70, 0x1200
	v_readlane_b32 s3, v242, 8
	s_addc_u32 s11, s71, 0
	s_mul_i32 s3, s75, s3
	s_add_u32 s12, s70, 0x1300
	s_mul_i32 s3, s3, s74
	s_addc_u32 s13, s71, 0
	s_mov_b32 s20, 1
	v_mov_b32_e32 v17, 0
	s_branch .LBB0_1185

.LBB0_1282:
	s_cmp_gt_i32 s73, 12
	s_cselect_b64 s[0:1], -1, 0
	s_and_b64 s[4:5], s[6:7], s[0:1]
	s_andn2_b64 vcc, exec, s[4:5]
	s_cbranch_vccnz .LBB0_1346
	s_cmp_gt_i32 s72, -1
	s_mov_b64 s[4:5], -1
	s_cbranch_scc0 .LBB0_1333
	s_waitcnt vmcnt(0)
	v_cmp_eq_u32_e32 vcc, 0, v143
	s_waitcnt vmcnt(0) lgkmcnt(0)
	s_barrier
	s_and_saveexec_b64 s[4:5], vcc
	s_cbranch_execz .LBB0_1332
	s_mov_b32 s98, 10
	s_branch .Lsbar
	v_readlane_b32 s3, v242, 11
	s_waitcnt vmcnt(0) expcnt(0) lgkmcnt(0)
	s_nop 0
	v_mov_b32_e32 v1, s3
	ds_read_b32 v3, v1
	ds_read_b32 v1, v1 offset:4
	s_waitcnt lgkmcnt(1)
	v_cmp_ne_u32_e32 vcc, 0, v3
	s_cbranch_vccnz .LBB0_1300
	s_add_u32 s6, s70, 0x1000
	s_addc_u32 s7, s71, 0
	s_add_u32 s8, s70, 0x1100
	s_addc_u32 s9, s71, 0
	s_add_u32 s10, s70, 0x1200
	v_readlane_b32 s3, v242, 8
	s_addc_u32 s11, s71, 0
	s_mul_i32 s3, s75, s3
	s_add_u32 s12, s70, 0x1300
	s_mul_i32 s3, s3, s74
	s_addc_u32 s13, s71, 0
	s_mov_b32 s20, 1
	v_mov_b32_e32 v17, 0
	s_branch .LBB0_1288

.LBB0_1353:
	s_cmp_gt_i32 s73, 13
	s_cselect_b64 s[4:5], -1, 0
	s_and_b64 s[0:1], s[0:1], s[4:5]
	s_andn2_b64 vcc, exec, s[0:1]
	s_cbranch_vccnz .LBB0_1417
	s_cmp_gt_i32 s72, -1
	s_mov_b64 s[0:1], -1
	s_cbranch_scc0 .LBB0_1404
	s_waitcnt vmcnt(0)
	v_cmp_eq_u32_e32 vcc, 0, v143
	s_waitcnt vmcnt(0) lgkmcnt(0)
	s_barrier
	s_and_saveexec_b64 s[0:1], vcc
	s_cbranch_execz .LBB0_1403
	s_mov_b32 s98, 11
	s_branch .Lsbar
	v_readlane_b32 s3, v242, 11
	s_waitcnt vmcnt(0) expcnt(0) lgkmcnt(0)
	s_nop 0
	v_mov_b32_e32 v1, s3
	ds_read_b32 v3, v1
	ds_read_b32 v1, v1 offset:4
	s_waitcnt lgkmcnt(1)
	v_cmp_ne_u32_e32 vcc, 0, v3
	s_cbranch_vccnz .LBB0_1371
	s_add_u32 s6, s70, 0x1000
	s_addc_u32 s7, s71, 0
	s_add_u32 s8, s70, 0x1100
	s_addc_u32 s9, s71, 0
	s_add_u32 s10, s70, 0x1200
	v_readlane_b32 s3, v242, 8
	s_addc_u32 s11, s71, 0
	s_mul_i32 s3, s75, s3
	s_add_u32 s12, s70, 0x1300
	s_mul_i32 s3, s3, s74
	s_addc_u32 s13, s71, 0
	s_mov_b32 s20, 1
	v_mov_b32_e32 v17, 0
	s_branch .LBB0_1359

.LBB0_1434:
	s_cmp_gt_i32 s73, 14
	s_cselect_b64 s[0:1], -1, 0
	s_and_b64 s[4:5], s[4:5], s[0:1]
	s_andn2_b64 vcc, exec, s[4:5]
	v_readlane_b32 s96, v242, 55
	v_readlane_b32 s97, v242, 56
	s_cbranch_vccnz .LBB0_1498
	s_cmp_gt_i32 s72, -1
	s_mov_b64 s[4:5], -1
	s_cbranch_scc0 .LBB0_1485
	s_waitcnt vmcnt(0)
	v_cmp_eq_u32_e32 vcc, 0, v143
	s_waitcnt vmcnt(0) lgkmcnt(0)
	s_barrier
	s_and_saveexec_b64 s[4:5], vcc
	s_cbranch_execz .LBB0_1484
	s_mov_b32 s98, 12
	s_branch .Lsbar
	v_readlane_b32 s3, v242, 11
	s_waitcnt vmcnt(0) expcnt(0) lgkmcnt(0)
	s_nop 0
	v_mov_b32_e32 v1, s3
	ds_read_b32 v3, v1
	ds_read_b32 v1, v1 offset:4
	s_waitcnt lgkmcnt(1)
	v_cmp_ne_u32_e32 vcc, 0, v3
	s_cbranch_vccnz .LBB0_1452
	s_add_u32 s6, s70, 0x1000
	s_addc_u32 s7, s71, 0
	s_add_u32 s8, s70, 0x1100
	s_addc_u32 s9, s71, 0
	s_add_u32 s10, s70, 0x1200
	v_readlane_b32 s3, v242, 8
	s_addc_u32 s11, s71, 0
	s_mul_i32 s3, s75, s3
	s_add_u32 s12, s70, 0x1300
	s_mul_i32 s3, s3, s74
	s_addc_u32 s13, s71, 0
	s_mov_b32 s20, 1
	v_mov_b32_e32 v17, 0
	s_branch .LBB0_1440

.LBB0_1538:
	s_cmp_gt_i32 s73, 15
	s_cselect_b64 s[0:1], -1, 0
	s_and_b64 s[2:3], s[4:5], s[0:1]
	s_andn2_b64 vcc, exec, s[2:3]
	s_cbranch_vccnz .LBB0_1602
	s_cmp_gt_i32 s72, -1
	s_mov_b64 s[2:3], -1
	s_cbranch_scc0 .LBB0_1589
	s_waitcnt vmcnt(0)
	v_cmp_eq_u32_e32 vcc, 0, v143
	s_waitcnt vmcnt(0) lgkmcnt(0)
	s_barrier
	s_and_saveexec_b64 s[2:3], vcc
	s_cbranch_execz .LBB0_1588
	s_mov_b32 s98, 13
	s_branch .Lsbar
	v_readlane_b32 s4, v242, 11
	s_waitcnt vmcnt(0) expcnt(0) lgkmcnt(0)
	s_nop 0
	v_mov_b32_e32 v1, s4
	ds_read_b32 v3, v1
	ds_read_b32 v1, v1 offset:4
	s_waitcnt lgkmcnt(1)
	v_cmp_ne_u32_e32 vcc, 0, v3
	s_cbranch_vccnz .LBB0_1556
	v_readlane_b32 s4, v242, 8
	s_mul_i32 s18, s75, s4
	s_add_u32 s4, s70, 0x1000
	s_addc_u32 s5, s71, 0
	s_add_u32 s6, s70, 0x1100
	s_addc_u32 s7, s71, 0
	s_add_u32 s8, s70, 0x1200
	s_addc_u32 s9, s71, 0
	s_add_u32 s10, s70, 0x1300
	s_mul_i32 s18, s18, s74
	s_addc_u32 s11, s71, 0
	s_mov_b32 s19, 1
	v_mov_b32_e32 v17, 0
	s_branch .LBB0_1544
